# flip deletion combined with the G K-loop B0 fragment read rebalancing
# speedup vs baseline: 1.0105x; 1.0105x over previous
; #define LDA(dst, b, h) for (int m = 0; m < 4; ++m) for (int k = 0; k < 2; ++k) \
;     dst[m][k] = *reinterpret_cast<const bf16x8*>((char*)SA(b, h) + lds_byte(wr * 64 + m * 16 + fr, k * 32 + fq * 8))
; #define LDB(dst, b, h) for (int n = 0; n < 2; ++n) for (int k = 0; k < 2; ++k) \
;     dst[n][k] = *reinterpret_cast<const bf16x8*>((char*)SB(b, h) + lds_byte(wc * 32 + n * 16 + fr, k * 32 + fq * 8))
; #define MMA(ai, bj, At_, Bt_) do { __builtin_amdgcn_s_setprio(1); \
;     for (int m = 0; m < 4; ++m) for (int n = 0; n < 2; ++n) for (int k = 0; k < 2; ++k) \
;       acc[ai][bj][m][n] = MFMA16(Bt_[n][k], At_[m][k], acc[ai][bj][m][n]); \
;     __builtin_amdgcn_s_setprio(0); } while (0)
; #define WAIT_L(n) asm volatile("s_waitcnt lgkmcnt(" #n ")" ::: "memory")
; #define BAR __builtin_amdgcn_s_barrier()
; #define SCHED __builtin_amdgcn_sched_barrier(0)
; template <int PART  , bool SYNC_FIRST = true>
; __device__ __forceinline__ void kloop_t(const u16* __restrict__ A, int lda, const u16* __restrict__ Bt, int ldb, int K, Acc& acc, const int wv) {
;     ...
;     LDB(B0, 0, 0); SCHED; LDA(At, 0, 0); STAGE(SA(1, 1), A, lda, HALF, t + 1);
;     WAIT_L(8); BAR; WAIT_L(0); MMA(0, 0, At, B0); BAR; SCHED;
;     LDB(B1, 0, 1); STAGE(SB(0, 0), Bt, ldb, 0, t + 2);
;     BAR; WAIT_L(0); MMA(0, 1, At, B1); BAR;
;     LDA(At, 0, 1); STAGE(SA(0, 0), A, lda, 0, t + 2);
;     BAR; WAIT_L(0); MMA(1, 0, At, B0); BAR; SCHED;
.LBB0_1139:
	s_add_u32 s44, s42, s56
	v_mov_b32_e32 v170, v131
	v_mov_b32_e32 v128, v130
	s_addc_u32 s45, s43, 0
	ds_read_b128 v[190:193], v132
	ds_read_b128 v[194:197], v133
	ds_read_b128 v[198:201], v134
	ds_read_b128 v[202:205], v135
	ds_read_b128 v[206:209], v136
	ds_read_b128 v[210:213], v137
	ds_read_b128 v[214:217], v138
	ds_read_b128 v[218:221], v139
	v_mov_b32_e32 v171, v129
	v_lshl_add_u64 v[168:169], s[44:45], 0, v[128:129]
	v_lshl_add_u64 v[172:173], v[168:169], 0, s[24:25]
	v_add_u32_e32 v168, 0xc000, v144
	v_add_u32_e32 v169, 0xe000, v144
	v_readfirstlane_b32 s52, v168
	s_mov_b32 m0, s52
	v_lshl_add_u64 v[170:171], s[44:45], 0, v[170:171]
	v_readfirstlane_b32 s52, v169
	global_load_lds_dwordx4 v[172:173], off
	v_lshl_add_u64 v[170:171], v[170:171], 0, s[24:25]
	s_mov_b32 m0, s52
	s_nop 0
	global_load_lds_dwordx4 v[170:171], off
	s_waitcnt lgkmcnt(8)
	s_barrier
	s_waitcnt lgkmcnt(0)
	s_waitcnt lgkmcnt(0)
	v_mfma_f32_16x16x32_bf16 v[124:127], v[174:177], v[190:193], v[124:127]
	v_mfma_f32_16x16x32_bf16 v[120:123], v[182:185], v[190:193], v[120:123]
	v_mfma_f32_16x16x32_bf16 v[116:119], v[174:177], v[198:201], v[116:119]
	v_mfma_f32_16x16x32_bf16 v[112:115], v[182:185], v[198:201], v[112:115]
	v_mfma_f32_16x16x32_bf16 v[108:111], v[174:177], v[206:209], v[108:111]
	v_mfma_f32_16x16x32_bf16 v[104:107], v[182:185], v[206:209], v[104:107]
	v_mfma_f32_16x16x32_bf16 v[100:103], v[174:177], v[214:217], v[100:103]
	v_mfma_f32_16x16x32_bf16 v[96:99], v[182:185], v[214:217], v[96:99]
	v_mfma_f32_16x16x32_bf16 v[124:127], v[178:181], v[194:197], v[124:127]
	v_mfma_f32_16x16x32_bf16 v[120:123], v[186:189], v[194:197], v[120:123]
	v_mfma_f32_16x16x32_bf16 v[116:119], v[178:181], v[202:205], v[116:119]
	v_mfma_f32_16x16x32_bf16 v[112:115], v[186:189], v[202:205], v[112:115]
	v_mfma_f32_16x16x32_bf16 v[108:111], v[178:181], v[210:213], v[108:111]
	v_mfma_f32_16x16x32_bf16 v[104:107], v[186:189], v[210:213], v[104:107]
	v_mfma_f32_16x16x32_bf16 v[100:103], v[178:181], v[218:221], v[100:103]
	v_mfma_f32_16x16x32_bf16 v[96:99], v[186:189], v[218:221], v[96:99]
	s_barrier
	s_add_u32 s52, s42, s55
	v_add_u32_e32 v170, v157, v160
	v_add_u32_e32 v172, v157, v162
	v_mov_b32_e32 v238, v131
	v_mov_b32_e32 v128, v130
	s_addc_u32 s53, s43, 0
	v_add_u32_e32 v171, v157, v161
	ds_read_b128 v[222:225], v170
	ds_read_b128 v[226:229], v171
	v_add_u32_e32 v173, v157, v163
	ds_read_b128 v[230:233], v172
	ds_read_b128 v[234:237], v173
	v_readfirstlane_b32 s87, v142
	v_lshl_add_u64 v[240:241], s[52:53], 0, v[128:129]
	v_mov_b32_e32 v239, v129
	v_lshl_add_u64 v[240:241], v[240:241], 0, s[26:27]
	s_mov_b32 m0, s87
	v_lshl_add_u64 v[238:239], s[52:53], 0, v[238:239]
	v_readfirstlane_b32 s87, v143
	global_load_lds_dwordx4 v[240:241], off
	v_lshl_add_u64 v[238:239], v[238:239], 0, s[26:27]
	s_mov_b32 m0, s87
	s_nop 0
	global_load_lds_dwordx4 v[238:239], off
	s_barrier
	s_waitcnt lgkmcnt(0)
	s_waitcnt lgkmcnt(0)
	v_mfma_f32_16x16x32_bf16 v[92:95], v[222:225], v[190:193], v[92:95]
	v_mfma_f32_16x16x32_bf16 v[88:91], v[230:233], v[190:193], v[88:91]
	v_mfma_f32_16x16x32_bf16 v[84:87], v[222:225], v[198:201], v[84:87]
	v_mfma_f32_16x16x32_bf16 v[80:83], v[230:233], v[198:201], v[80:83]
	v_mfma_f32_16x16x32_bf16 v[76:79], v[222:225], v[206:209], v[76:79]
	v_mfma_f32_16x16x32_bf16 v[72:75], v[230:233], v[206:209], v[72:75]
	v_mfma_f32_16x16x32_bf16 v[68:71], v[222:225], v[214:217], v[68:71]
	v_mfma_f32_16x16x32_bf16 v[64:67], v[230:233], v[214:217], v[64:67]
	v_mfma_f32_16x16x32_bf16 v[92:95], v[226:229], v[194:197], v[92:95]
	v_mfma_f32_16x16x32_bf16 v[88:91], v[234:237], v[194:197], v[88:91]
	v_mfma_f32_16x16x32_bf16 v[84:87], v[226:229], v[202:205], v[84:87]
	v_mfma_f32_16x16x32_bf16 v[80:83], v[234:237], v[202:205], v[80:83]
	v_mfma_f32_16x16x32_bf16 v[76:79], v[226:229], v[210:213], v[76:79]
	v_mfma_f32_16x16x32_bf16 v[72:75], v[234:237], v[210:213], v[72:75]
	v_mfma_f32_16x16x32_bf16 v[68:71], v[226:229], v[218:221], v[68:71]
	v_mfma_f32_16x16x32_bf16 v[64:67], v[234:237], v[218:221], v[64:67]
	v_mov_b32_e32 v238, v131
	v_mov_b32_e32 v128, v130
	s_barrier
	ds_read_b128 v[190:193], v132 offset:16384
	ds_read_b128 v[194:197], v133 offset:16384
	ds_read_b128 v[198:201], v134 offset:16384
	ds_read_b128 v[202:205], v135 offset:16384
	ds_read_b128 v[206:209], v136 offset:16384
	ds_read_b128 v[210:213], v137 offset:16384
	ds_read_b128 v[214:217], v138 offset:16384
	ds_read_b128 v[218:221], v139 offset:16384
	v_readfirstlane_b32 s87, v144
	v_lshl_add_u64 v[240:241], s[44:45], 0, v[128:129]
	v_mov_b32_e32 v239, v129
	v_lshl_add_u64 v[240:241], v[240:241], 0, s[28:29]
	s_mov_b32 m0, s87
	v_lshl_add_u64 v[238:239], s[44:45], 0, v[238:239]
	v_readfirstlane_b32 s87, v145
	global_load_lds_dwordx4 v[240:241], off
	v_lshl_add_u64 v[238:239], v[238:239], 0, s[28:29]
	s_mov_b32 m0, s87
	s_nop 0
	global_load_lds_dwordx4 v[238:239], off
	s_waitcnt vmcnt(10)
	s_barrier
	s_waitcnt lgkmcnt(0)
	s_waitcnt lgkmcnt(0)
	v_mfma_f32_16x16x32_bf16 v[60:63], v[174:177], v[190:193], v[60:63]
	v_mfma_f32_16x16x32_bf16 v[56:59], v[182:185], v[190:193], v[56:59]
	v_mfma_f32_16x16x32_bf16 v[52:55], v[174:177], v[198:201], v[52:55]
	v_mfma_f32_16x16x32_bf16 v[48:51], v[182:185], v[198:201], v[48:51]
	v_mfma_f32_16x16x32_bf16 v[44:47], v[174:177], v[206:209], v[44:47]
	v_mfma_f32_16x16x32_bf16 v[40:43], v[182:185], v[206:209], v[40:43]
	v_mfma_f32_16x16x32_bf16 v[36:39], v[174:177], v[214:217], v[36:39]
	v_mfma_f32_16x16x32_bf16 v[32:35], v[182:185], v[214:217], v[32:35]
	v_mfma_f32_16x16x32_bf16 v[60:63], v[178:181], v[194:197], v[60:63]
	v_mfma_f32_16x16x32_bf16 v[56:59], v[186:189], v[194:197], v[56:59]
	v_mfma_f32_16x16x32_bf16 v[52:55], v[178:181], v[202:205], v[52:55]
	v_mfma_f32_16x16x32_bf16 v[48:51], v[186:189], v[202:205], v[48:51]
	v_mfma_f32_16x16x32_bf16 v[44:47], v[178:181], v[210:213], v[44:47]
	v_mfma_f32_16x16x32_bf16 v[40:43], v[186:189], v[210:213], v[40:43]
	v_mfma_f32_16x16x32_bf16 v[36:39], v[178:181], v[218:221], v[36:39]
	v_mfma_f32_16x16x32_bf16 v[32:35], v[186:189], v[218:221], v[32:35]
	s_barrier
; #define LDA(dst, b, h) for (int m = 0; m < 4; ++m) for (int k = 0; k < 2; ++k) \
;     dst[m][k] = *reinterpret_cast<const bf16x8*>((char*)SA(b, h) + lds_byte(wr * 64 + m * 16 + fr, k * 32 + fq * 8))
; #define LDB(dst, b, h) for (int n = 0; n < 2; ++n) for (int k = 0; k < 2; ++k) \
;     dst[n][k] = *reinterpret_cast<const bf16x8*>((char*)SB(b, h) + lds_byte(wc * 32 + n * 16 + fr, k * 32 + fq * 8))
; #define MMA(ai, bj, At_, Bt_) do { __builtin_amdgcn_s_setprio(1); \
;     for (int m = 0; m < 4; ++m) for (int n = 0; n < 2; ++n) for (int k = 0; k < 2; ++k) \
;       acc[ai][bj][m][n] = MFMA16(Bt_[n][k], At_[m][k], acc[ai][bj][m][n]); \
;     __builtin_amdgcn_s_setprio(0); } while (0)
; #define WAIT_V(n) asm volatile("s_waitcnt vmcnt(" #n ")" ::: "memory")
; #define WAIT_L(n) asm volatile("s_waitcnt lgkmcnt(" #n ")" ::: "memory")
; #define BAR __builtin_amdgcn_s_barrier()
; #define SCHED __builtin_amdgcn_sched_barrier(0)
; template <int PART  , bool SYNC_FIRST = true>
; __device__ __forceinline__ void kloop_t(const u16* __restrict__ A, int lda, const u16* __restrict__ Bt, int ldb, int K, Acc& acc, const int wv) {
;     ...
;     STAGE(SB(0, 1), Bt, ldb, HALF, t + 2);
;     WAIT_V(6); BAR; MMA(1, 1, At, B1); BAR;
;     LDB(B0, 1, 0); SCHED; LDA(At, 1, 0); STAGE(SA(0, 1), A, lda, HALF, t + 2);
;     WAIT_L(8); BAR; WAIT_L(0); MMA(0, 0, At, B0); BAR; SCHED;
;     LDB(B1, 1, 1); STAGE(SB(1, 0), Bt, ldb, 0, t + 3);
;     BAR; WAIT_L(0); MMA(0, 1, At, B1); BAR;
;     LDA(At, 1, 1); STAGE(SA(1, 0), A, lda, 0, t + 3);
;     BAR; WAIT_L(0); MMA(1, 0, At, B0); BAR; SCHED;
	v_mov_b32_e32 v174, v131
	v_mov_b32_e32 v128, v130
	v_readfirstlane_b32 s87, v146
	v_lshl_add_u64 v[176:177], s[52:53], 0, v[128:129]
	v_mov_b32_e32 v175, v129
	v_lshl_add_u64 v[176:177], v[176:177], 0, s[30:31]
	s_mov_b32 m0, s87
	v_lshl_add_u64 v[174:175], s[52:53], 0, v[174:175]
	v_readfirstlane_b32 s87, v147
	global_load_lds_dwordx4 v[176:177], off
	v_lshl_add_u64 v[174:175], v[174:175], 0, s[30:31]
	s_mov_b32 m0, s87
	s_nop 0
	global_load_lds_dwordx4 v[174:175], off
	v_add_u32_e32 v174, v158, v160
	v_add_u32_e32 v175, v158, v161
	v_add_u32_e32 v176, v158, v162
	v_add_u32_e32 v177, v158, v163
	s_waitcnt vmcnt(6)
	s_barrier
	v_mfma_f32_16x16x32_bf16 v[28:31], v[222:225], v[190:193], v[28:31]
	v_mfma_f32_16x16x32_bf16 v[24:27], v[230:233], v[190:193], v[24:27]
	ds_read_b128 v[182:185], v174
	ds_read_b128 v[186:189], v175
	ds_read_b128 v[190:193], v176
	v_mfma_f32_16x16x32_bf16 v[20:23], v[222:225], v[198:201], v[20:23]
	v_mfma_f32_16x16x32_bf16 v[16:19], v[230:233], v[198:201], v[16:19]
	v_mfma_f32_16x16x32_bf16 v[12:15], v[222:225], v[206:209], v[12:15]
	v_mfma_f32_16x16x32_bf16 v[8:11], v[230:233], v[206:209], v[8:11]
	v_mfma_f32_16x16x32_bf16 v[4:7], v[222:225], v[214:217], v[4:7]
	v_mfma_f32_16x16x32_bf16 v[0:3], v[230:233], v[214:217], v[0:3]
	v_mfma_f32_16x16x32_bf16 v[28:31], v[226:229], v[194:197], v[28:31]
	v_mfma_f32_16x16x32_bf16 v[24:27], v[234:237], v[194:197], v[24:27]
	ds_read_b128 v[194:197], v177
	v_mfma_f32_16x16x32_bf16 v[20:23], v[226:229], v[202:205], v[20:23]
	v_mfma_f32_16x16x32_bf16 v[16:19], v[234:237], v[202:205], v[16:19]
	v_mfma_f32_16x16x32_bf16 v[12:15], v[226:229], v[210:213], v[12:15]
	v_mfma_f32_16x16x32_bf16 v[8:11], v[234:237], v[210:213], v[8:11]
	v_mfma_f32_16x16x32_bf16 v[4:7], v[226:229], v[218:221], v[4:7]
	v_mfma_f32_16x16x32_bf16 v[0:3], v[234:237], v[218:221], v[0:3]
	s_barrier
	v_mov_b32_e32 v178, v131
	v_mov_b32_e32 v128, v130
	ds_read_b128 v[198:201], v132 offset:32768
	ds_read_b128 v[202:205], v133 offset:32768
	ds_read_b128 v[206:209], v134 offset:32768
	ds_read_b128 v[210:213], v135 offset:32768
	ds_read_b128 v[214:217], v136 offset:32768
	ds_read_b128 v[218:221], v137 offset:32768
	ds_read_b128 v[222:225], v138 offset:32768
	ds_read_b128 v[226:229], v139 offset:32768
	v_readfirstlane_b32 s87, v148
	v_lshl_add_u64 v[180:181], s[44:45], 0, v[128:129]
	v_mov_b32_e32 v179, v129
	v_lshl_add_u64 v[180:181], v[180:181], 0, s[34:35]
	s_mov_b32 m0, s87
	v_lshl_add_u64 v[178:179], s[44:45], 0, v[178:179]
	v_readfirstlane_b32 s87, v149
	global_load_lds_dwordx4 v[180:181], off
	v_lshl_add_u64 v[178:179], v[178:179], 0, s[34:35]
	s_mov_b32 m0, s87
	s_nop 0
	global_load_lds_dwordx4 v[178:179], off
	s_waitcnt lgkmcnt(8)
	s_barrier
	s_waitcnt lgkmcnt(0)
	s_waitcnt lgkmcnt(0)
	v_mfma_f32_16x16x32_bf16 v[124:127], v[182:185], v[198:201], v[124:127]
	v_mfma_f32_16x16x32_bf16 v[120:123], v[190:193], v[198:201], v[120:123]
	v_mfma_f32_16x16x32_bf16 v[116:119], v[182:185], v[206:209], v[116:119]
	v_mfma_f32_16x16x32_bf16 v[112:115], v[190:193], v[206:209], v[112:115]
	v_mfma_f32_16x16x32_bf16 v[108:111], v[182:185], v[214:217], v[108:111]
	v_mfma_f32_16x16x32_bf16 v[104:107], v[190:193], v[214:217], v[104:107]
	v_mfma_f32_16x16x32_bf16 v[100:103], v[182:185], v[222:225], v[100:103]
	v_mfma_f32_16x16x32_bf16 v[96:99], v[190:193], v[222:225], v[96:99]
	v_mfma_f32_16x16x32_bf16 v[124:127], v[186:189], v[202:205], v[124:127]
	v_mfma_f32_16x16x32_bf16 v[120:123], v[194:197], v[202:205], v[120:123]
	v_mfma_f32_16x16x32_bf16 v[116:119], v[186:189], v[210:213], v[116:119]
	v_mfma_f32_16x16x32_bf16 v[112:115], v[194:197], v[210:213], v[112:115]
	v_mfma_f32_16x16x32_bf16 v[108:111], v[186:189], v[218:221], v[108:111]
	v_mfma_f32_16x16x32_bf16 v[104:107], v[194:197], v[218:221], v[104:107]
	v_mfma_f32_16x16x32_bf16 v[100:103], v[186:189], v[226:229], v[100:103]
	v_mfma_f32_16x16x32_bf16 v[96:99], v[194:197], v[226:229], v[96:99]
	s_barrier
	v_add_u32_e32 v178, v159, v160
	v_add_u32_e32 v180, v159, v162
	v_mov_b32_e32 v246, v131
	v_mov_b32_e32 v128, v130
	v_add_u32_e32 v179, v159, v161
	ds_read_b128 v[230:233], v178
	ds_read_b128 v[234:237], v179
	v_add_u32_e32 v181, v159, v163
	ds_read_b128 v[238:241], v180
	ds_read_b128 v[242:245], v181
	v_readfirstlane_b32 s87, v150
	v_lshl_add_u64 v[248:249], s[52:53], 0, v[128:129]
	v_mov_b32_e32 v247, v129
	v_lshl_add_u64 v[248:249], v[248:249], 0, s[36:37]
	s_mov_b32 m0, s87
	v_lshl_add_u64 v[246:247], s[52:53], 0, v[246:247]
	v_readfirstlane_b32 s87, v151
	global_load_lds_dwordx4 v[248:249], off
	v_lshl_add_u64 v[246:247], v[246:247], 0, s[36:37]
	s_mov_b32 m0, s87
	s_nop 0
	global_load_lds_dwordx4 v[246:247], off
	s_barrier
	s_waitcnt lgkmcnt(0)
	s_waitcnt lgkmcnt(0)
	v_mfma_f32_16x16x32_bf16 v[92:95], v[230:233], v[198:201], v[92:95]
	v_mfma_f32_16x16x32_bf16 v[88:91], v[238:241], v[198:201], v[88:91]
	v_mfma_f32_16x16x32_bf16 v[84:87], v[230:233], v[206:209], v[84:87]
	v_mfma_f32_16x16x32_bf16 v[80:83], v[238:241], v[206:209], v[80:83]
	v_mfma_f32_16x16x32_bf16 v[76:79], v[230:233], v[214:217], v[76:79]
	v_mfma_f32_16x16x32_bf16 v[72:75], v[238:241], v[214:217], v[72:75]
	v_mfma_f32_16x16x32_bf16 v[68:71], v[230:233], v[222:225], v[68:71]
	v_mfma_f32_16x16x32_bf16 v[64:67], v[238:241], v[222:225], v[64:67]
	v_mfma_f32_16x16x32_bf16 v[92:95], v[234:237], v[202:205], v[92:95]
	v_mfma_f32_16x16x32_bf16 v[88:91], v[242:245], v[202:205], v[88:91]
	v_mfma_f32_16x16x32_bf16 v[84:87], v[234:237], v[210:213], v[84:87]
	v_mfma_f32_16x16x32_bf16 v[80:83], v[242:245], v[210:213], v[80:83]
	v_mfma_f32_16x16x32_bf16 v[76:79], v[234:237], v[218:221], v[76:79]
	v_mfma_f32_16x16x32_bf16 v[72:75], v[242:245], v[218:221], v[72:75]
	v_mfma_f32_16x16x32_bf16 v[68:71], v[234:237], v[226:229], v[68:71]
	v_mfma_f32_16x16x32_bf16 v[64:67], v[242:245], v[226:229], v[64:67]
	v_mov_b32_e32 v246, v131
	v_mov_b32_e32 v128, v130
	s_barrier
; #define LDA(dst, b, h) for (int m = 0; m < 4; ++m) for (int k = 0; k < 2; ++k) \
;     dst[m][k] = *reinterpret_cast<const bf16x8*>((char*)SA(b, h) + lds_byte(wr * 64 + m * 16 + fr, k * 32 + fq * 8))
; #define LDB(dst, b, h) for (int n = 0; n < 2; ++n) for (int k = 0; k < 2; ++k) \
;     dst[n][k] = *reinterpret_cast<const bf16x8*>((char*)SB(b, h) + lds_byte(wc * 32 + n * 16 + fr, k * 32 + fq * 8))
; #define MMA(ai, bj, At_, Bt_) do { __builtin_amdgcn_s_setprio(1); \
;     for (int m = 0; m < 4; ++m) for (int n = 0; n < 2; ++n) for (int k = 0; k < 2; ++k) \
;       acc[ai][bj][m][n] = MFMA16(Bt_[n][k], At_[m][k], acc[ai][bj][m][n]); \
;     __builtin_amdgcn_s_setprio(0); } while (0)
; #define WAIT_V(n) asm volatile("s_waitcnt vmcnt(" #n ")" ::: "memory")
; #define WAIT_L(n) asm volatile("s_waitcnt lgkmcnt(" #n ")" ::: "memory")
; #define BAR __builtin_amdgcn_s_barrier()
; template <int PART  , bool SYNC_FIRST = true>
; __device__ __forceinline__ void kloop_t(const u16* __restrict__ A, int lda, const u16* __restrict__ Bt, int ldb, int K, Acc& acc, const int wv) {
;     ...
;     STAGE(SB(1, 1), Bt, ldb, HALF, t + 3);
;     WAIT_V(6); BAR; MMA(1, 1, At, B1); BAR;
;   }
;   { LDB(B0, 0, 0); LDA(At, 0, 0); STAGE(SA(1, 1), A, lda, HALF, nt - 1);
;     BAR; WAIT_L(0); MMA(0, 0, At, B0); BAR;
	ds_read_b128 v[198:201], v132 offset:49152
	ds_read_b128 v[202:205], v133 offset:49152
	ds_read_b128 v[206:209], v134 offset:49152
	ds_read_b128 v[210:213], v135 offset:49152
	ds_read_b128 v[214:217], v136 offset:49152
	ds_read_b128 v[218:221], v137 offset:49152
	ds_read_b128 v[222:225], v138 offset:49152
	ds_read_b128 v[226:229], v139 offset:49152
	v_readfirstlane_b32 s87, v152
	v_lshl_add_u64 v[248:249], s[44:45], 0, v[128:129]
	v_mov_b32_e32 v247, v129
	v_lshl_add_u64 v[248:249], v[248:249], 0, s[38:39]
	s_mov_b32 m0, s87
	v_lshl_add_u64 v[246:247], s[44:45], 0, v[246:247]
	v_readfirstlane_b32 s44, v153
	global_load_lds_dwordx4 v[248:249], off
	v_lshl_add_u64 v[246:247], v[246:247], 0, s[38:39]
	s_mov_b32 m0, s44
	s_nop 0
	global_load_lds_dwordx4 v[246:247], off
	s_waitcnt vmcnt(10)
	s_barrier
	s_waitcnt lgkmcnt(0)
	s_waitcnt lgkmcnt(0)
	v_mfma_f32_16x16x32_bf16 v[60:63], v[182:185], v[198:201], v[60:63]
	v_mfma_f32_16x16x32_bf16 v[56:59], v[190:193], v[198:201], v[56:59]
	v_mfma_f32_16x16x32_bf16 v[52:55], v[182:185], v[206:209], v[52:55]
	v_mfma_f32_16x16x32_bf16 v[48:51], v[190:193], v[206:209], v[48:51]
	v_mfma_f32_16x16x32_bf16 v[44:47], v[182:185], v[214:217], v[44:47]
	v_mfma_f32_16x16x32_bf16 v[40:43], v[190:193], v[214:217], v[40:43]
	v_mfma_f32_16x16x32_bf16 v[36:39], v[182:185], v[222:225], v[36:39]
	v_mfma_f32_16x16x32_bf16 v[32:35], v[190:193], v[222:225], v[32:35]
	v_mfma_f32_16x16x32_bf16 v[60:63], v[186:189], v[202:205], v[60:63]
	v_mfma_f32_16x16x32_bf16 v[56:59], v[194:197], v[202:205], v[56:59]
	v_mfma_f32_16x16x32_bf16 v[52:55], v[186:189], v[210:213], v[52:55]
	v_mfma_f32_16x16x32_bf16 v[48:51], v[194:197], v[210:213], v[48:51]
	v_mfma_f32_16x16x32_bf16 v[44:47], v[186:189], v[218:221], v[44:47]
	v_mfma_f32_16x16x32_bf16 v[40:43], v[194:197], v[218:221], v[40:43]
	v_mfma_f32_16x16x32_bf16 v[36:39], v[186:189], v[226:229], v[36:39]
	v_mfma_f32_16x16x32_bf16 v[32:35], v[194:197], v[226:229], v[32:35]
	s_barrier
	v_mov_b32_e32 v182, v131
	v_mov_b32_e32 v128, v130
	v_readfirstlane_b32 s44, v154
	v_lshl_add_u64 v[184:185], s[52:53], 0, v[128:129]
	v_mov_b32_e32 v183, v129
	v_lshl_add_u64 v[184:185], v[184:185], 0, s[40:41]
	s_mov_b32 m0, s44
	v_lshl_add_u64 v[182:183], s[52:53], 0, v[182:183]
	v_readfirstlane_b32 s44, v155
	global_load_lds_dwordx4 v[184:185], off
	v_lshl_add_u64 v[182:183], v[182:183], 0, s[40:41]
	s_mov_b32 m0, s44
	s_nop 0
	global_load_lds_dwordx4 v[182:183], off
	s_waitcnt vmcnt(6)
	s_barrier
	v_mfma_f32_16x16x32_bf16 v[28:31], v[230:233], v[198:201], v[28:31]
	v_mfma_f32_16x16x32_bf16 v[24:27], v[238:241], v[198:201], v[24:27]
	ds_read_b128 v[174:177], v164
	ds_read_b128 v[178:181], v165
	ds_read_b128 v[182:185], v166
	ds_read_b128 v[186:189], v167
	v_mfma_f32_16x16x32_bf16 v[20:23], v[230:233], v[206:209], v[20:23]
	v_mfma_f32_16x16x32_bf16 v[16:19], v[238:241], v[206:209], v[16:19]
	v_mfma_f32_16x16x32_bf16 v[12:15], v[230:233], v[214:217], v[12:15]
	v_mfma_f32_16x16x32_bf16 v[8:11], v[238:241], v[214:217], v[8:11]
	v_mfma_f32_16x16x32_bf16 v[4:7], v[230:233], v[222:225], v[4:7]
	v_mfma_f32_16x16x32_bf16 v[0:3], v[238:241], v[222:225], v[0:3]
	v_mfma_f32_16x16x32_bf16 v[28:31], v[234:237], v[202:205], v[28:31]
	v_mfma_f32_16x16x32_bf16 v[24:27], v[242:245], v[202:205], v[24:27]
	v_mfma_f32_16x16x32_bf16 v[20:23], v[234:237], v[210:213], v[20:23]
	v_mfma_f32_16x16x32_bf16 v[16:19], v[242:245], v[210:213], v[16:19]
	v_mfma_f32_16x16x32_bf16 v[12:15], v[234:237], v[218:221], v[12:15]
	v_mfma_f32_16x16x32_bf16 v[8:11], v[242:245], v[218:221], v[8:11]
	v_mfma_f32_16x16x32_bf16 v[4:7], v[234:237], v[226:229], v[4:7]
	v_mfma_f32_16x16x32_bf16 v[0:3], v[242:245], v[226:229], v[0:3]
	s_add_i32 s57, s57, 2
	s_add_u32 s42, s42, 0x100
	s_addc_u32 s43, s43, 0
	s_cmp_lt_u32 s57, 60
	s_barrier
	s_cbranch_scc1 .LBB0_1139
	s_waitcnt lgkmcnt(0)
	v_add_u32_e32 v174, v158, v160
	v_add_u32_e32 v175, v158, v161
	v_add_u32_e32 v176, v158, v162
	v_add_u32_e32 v177, v158, v163
	v_add_u32_e32 v178, v159, v160
	v_add_u32_e32 v179, v159, v161
	v_add_u32_e32 v180, v159, v162
	v_add_u32_e32 v181, v159, v163
	s_add_u32 s4, s4, 0x101f80
	v_readfirstlane_b32 s42, v168
	s_addc_u32 s5, s5, 0
	s_mov_b32 m0, s42
	v_readfirstlane_b32 s42, v169
	ds_read_b128 v[142:145], v164
	ds_read_b128 v[146:149], v165
	ds_read_b128 v[150:153], v166
	ds_read_b128 v[154:157], v167
	ds_read_b128 v[158:161], v132
	ds_read_b128 v[162:165], v133
	ds_read_b128 v[182:185], v134
	ds_read_b128 v[186:189], v135
	ds_read_b128 v[190:193], v136
	ds_read_b128 v[194:197], v137
	ds_read_b128 v[198:201], v138
	ds_read_b128 v[202:205], v139
	s_nop 0
	global_load_lds_dwordx4 v130, s[4:5]
	s_mov_b32 m0, s42
	s_nop 0
	global_load_lds_dwordx4 v131, s[4:5]
	s_barrier
	s_waitcnt lgkmcnt(0)
	s_waitcnt lgkmcnt(0)
	v_mfma_f32_16x16x32_bf16 v[124:127], v[142:145], v[158:161], v[124:127]
	v_mfma_f32_16x16x32_bf16 v[120:123], v[150:153], v[158:161], v[120:123]
	v_mfma_f32_16x16x32_bf16 v[108:111], v[142:145], v[190:193], v[108:111]
	v_mfma_f32_16x16x32_bf16 v[104:107], v[150:153], v[190:193], v[104:107]
	v_mfma_f32_16x16x32_bf16 v[124:127], v[146:149], v[162:165], v[124:127]
	v_mfma_f32_16x16x32_bf16 v[120:123], v[154:157], v[162:165], v[120:123]
	v_mfma_f32_16x16x32_bf16 v[116:119], v[142:145], v[182:185], v[116:119]
	v_mfma_f32_16x16x32_bf16 v[112:115], v[150:153], v[182:185], v[112:115]
	v_mfma_f32_16x16x32_bf16 v[108:111], v[146:149], v[194:197], v[108:111]
	v_mfma_f32_16x16x32_bf16 v[104:107], v[154:157], v[194:197], v[104:107]
	v_mfma_f32_16x16x32_bf16 v[100:103], v[142:145], v[198:201], v[100:103]
	v_mfma_f32_16x16x32_bf16 v[96:99], v[150:153], v[198:201], v[96:99]
	v_mfma_f32_16x16x32_bf16 v[166:169], v[146:149], v[186:189], v[116:119]
	v_mfma_f32_16x16x32_bf16 v[206:209], v[154:157], v[186:189], v[112:115]
	v_mfma_f32_16x16x32_bf16 v[210:213], v[146:149], v[202:205], v[100:103]
	v_mfma_f32_16x16x32_bf16 v[214:217], v[154:157], v[202:205], v[96:99]
	s_barrier
; #define LDA(dst, b, h) for (int m = 0; m < 4; ++m) for (int k = 0; k < 2; ++k) \
;     dst[m][k] = *reinterpret_cast<const bf16x8*>((char*)SA(b, h) + lds_byte(wr * 64 + m * 16 + fr, k * 32 + fq * 8))
; #define LDB(dst, b, h) for (int n = 0; n < 2; ++n) for (int k = 0; k < 2; ++k) \
;     dst[n][k] = *reinterpret_cast<const bf16x8*>((char*)SB(b, h) + lds_byte(wc * 32 + n * 16 + fr, k * 32 + fq * 8))
; #define MMA(ai, bj, At_, Bt_) do { __builtin_amdgcn_s_setprio(1); \
;     for (int m = 0; m < 4; ++m) for (int n = 0; n < 2; ++n) for (int k = 0; k < 2; ++k) \
;       acc[ai][bj][m][n] = MFMA16(Bt_[n][k], At_[m][k], acc[ai][bj][m][n]); \
;     __builtin_amdgcn_s_setprio(0); } while (0)
; #define WAIT_V(n) asm volatile("s_waitcnt vmcnt(" #n ")" ::: "memory")
; #define WAIT_L(n) asm volatile("s_waitcnt lgkmcnt(" #n ")" ::: "memory")
; #define BAR __builtin_amdgcn_s_barrier()
; template <int PART  , bool SYNC_FIRST = true>
; __device__ __forceinline__ void kloop_t(const u16* __restrict__ A, int lda, const u16* __restrict__ Bt, int ldb, int K, Acc& acc, const int wv) {
;     ...
;     LDB(B1, 0, 1); BAR; WAIT_L(0); MMA(0, 1, At, B1); BAR;
;     LDA(At, 0, 1); WAIT_V(4); BAR; WAIT_L(0); MMA(1, 0, At, B0); MMA(1, 1, At, B1); BAR; }
;   { LDB(B0, 1, 0); LDA(At, 1, 0); WAIT_V(2); BAR; WAIT_L(0); MMA(0, 0, At, B0); BAR;
	s_nop 1
	ds_read_b128 v[96:99], v170
	ds_read_b128 v[100:103], v171
	ds_read_b128 v[112:115], v172
	ds_read_b128 v[116:119], v173
	s_barrier
	s_waitcnt lgkmcnt(0)
	s_waitcnt lgkmcnt(0)
	v_mfma_f32_16x16x32_bf16 v[92:95], v[96:99], v[158:161], v[92:95]
	v_mfma_f32_16x16x32_bf16 v[88:91], v[112:115], v[158:161], v[88:91]
	v_mfma_f32_16x16x32_bf16 v[76:79], v[96:99], v[190:193], v[76:79]
	v_mfma_f32_16x16x32_bf16 v[72:75], v[112:115], v[190:193], v[72:75]
	v_mfma_f32_16x16x32_bf16 v[92:95], v[100:103], v[162:165], v[92:95]
	v_mfma_f32_16x16x32_bf16 v[88:91], v[116:119], v[162:165], v[88:91]
	v_mfma_f32_16x16x32_bf16 v[84:87], v[96:99], v[182:185], v[84:87]
	v_mfma_f32_16x16x32_bf16 v[80:83], v[112:115], v[182:185], v[80:83]
	v_mfma_f32_16x16x32_bf16 v[76:79], v[100:103], v[194:197], v[76:79]
	v_mfma_f32_16x16x32_bf16 v[72:75], v[116:119], v[194:197], v[72:75]
	v_mfma_f32_16x16x32_bf16 v[68:71], v[96:99], v[198:201], v[68:71]
	v_mfma_f32_16x16x32_bf16 v[64:67], v[112:115], v[198:201], v[64:67]
	v_mfma_f32_16x16x32_bf16 v[158:161], v[100:103], v[186:189], v[84:87]
	v_mfma_f32_16x16x32_bf16 v[162:165], v[116:119], v[186:189], v[80:83]
	v_mfma_f32_16x16x32_bf16 v[170:173], v[100:103], v[202:205], v[68:71]
	v_mfma_f32_16x16x32_bf16 v[182:185], v[116:119], v[202:205], v[64:67]
	s_barrier
	s_nop 1
	ds_read_b128 v[64:67], v132 offset:16384
	ds_read_b128 v[68:71], v133 offset:16384
	ds_read_b128 v[80:83], v134 offset:16384
	ds_read_b128 v[84:87], v135 offset:16384
	ds_read_b128 v[186:189], v136 offset:16384
	ds_read_b128 v[190:193], v137 offset:16384
	ds_read_b128 v[194:197], v138 offset:16384
	ds_read_b128 v[198:201], v139 offset:16384
	s_waitcnt vmcnt(4)
	s_barrier
	s_waitcnt lgkmcnt(0)
	s_waitcnt lgkmcnt(0)
	v_mfma_f32_16x16x32_bf16 v[60:63], v[142:145], v[64:67], v[60:63]
	v_mfma_f32_16x16x32_bf16 v[56:59], v[150:153], v[64:67], v[56:59]
	v_mfma_f32_16x16x32_bf16 v[44:47], v[142:145], v[186:189], v[44:47]
	v_mfma_f32_16x16x32_bf16 v[40:43], v[150:153], v[186:189], v[40:43]
	v_mfma_f32_16x16x32_bf16 v[60:63], v[146:149], v[68:71], v[60:63]
	v_mfma_f32_16x16x32_bf16 v[56:59], v[154:157], v[68:71], v[56:59]
	v_mfma_f32_16x16x32_bf16 v[52:55], v[142:145], v[80:83], v[52:55]
	v_mfma_f32_16x16x32_bf16 v[48:51], v[150:153], v[80:83], v[48:51]
	v_mfma_f32_16x16x32_bf16 v[44:47], v[146:149], v[190:193], v[44:47]
	v_mfma_f32_16x16x32_bf16 v[40:43], v[154:157], v[190:193], v[40:43]
	v_mfma_f32_16x16x32_bf16 v[36:39], v[142:145], v[194:197], v[36:39]
	v_mfma_f32_16x16x32_bf16 v[32:35], v[150:153], v[194:197], v[32:35]
	v_mfma_f32_16x16x32_bf16 v[202:205], v[146:149], v[84:87], v[52:55]
	v_mfma_f32_16x16x32_bf16 v[218:221], v[154:157], v[84:87], v[48:51]
	v_mfma_f32_16x16x32_bf16 v[142:145], v[146:149], v[198:201], v[36:39]
	v_mfma_f32_16x16x32_bf16 v[146:149], v[154:157], v[198:201], v[32:35]
	v_mfma_f32_16x16x32_bf16 v[28:31], v[96:99], v[64:67], v[28:31]
	v_mfma_f32_16x16x32_bf16 v[24:27], v[112:115], v[64:67], v[24:27]
	v_mfma_f32_16x16x32_bf16 v[12:15], v[96:99], v[186:189], v[12:15]
	v_mfma_f32_16x16x32_bf16 v[8:11], v[112:115], v[186:189], v[8:11]
	v_mfma_f32_16x16x32_bf16 v[28:31], v[100:103], v[68:71], v[28:31]
	v_mfma_f32_16x16x32_bf16 v[24:27], v[116:119], v[68:71], v[24:27]
	v_mfma_f32_16x16x32_bf16 v[20:23], v[96:99], v[80:83], v[20:23]
	v_mfma_f32_16x16x32_bf16 v[16:19], v[112:115], v[80:83], v[16:19]
	v_mfma_f32_16x16x32_bf16 v[12:15], v[100:103], v[190:193], v[12:15]
	v_mfma_f32_16x16x32_bf16 v[8:11], v[116:119], v[190:193], v[8:11]
	v_mfma_f32_16x16x32_bf16 v[4:7], v[96:99], v[194:197], v[4:7]
	v_mfma_f32_16x16x32_bf16 v[0:3], v[112:115], v[194:197], v[0:3]
	v_mfma_f32_16x16x32_bf16 v[150:153], v[100:103], v[84:87], v[20:23]
	v_mfma_f32_16x16x32_bf16 v[154:157], v[116:119], v[84:87], v[16:19]
	v_mfma_f32_16x16x32_bf16 v[186:189], v[100:103], v[198:201], v[4:7]
	v_mfma_f32_16x16x32_bf16 v[190:193], v[116:119], v[198:201], v[0:3]
	s_barrier
	s_nop 1
	ds_read_b128 v[0:3], v174
	ds_read_b128 v[4:7], v175
	ds_read_b128 v[194:197], v176
	ds_read_b128 v[174:177], v177
	ds_read_b128 v[16:19], v132 offset:32768
	ds_read_b128 v[20:23], v133 offset:32768
	ds_read_b128 v[32:35], v134 offset:32768
	ds_read_b128 v[36:39], v135 offset:32768
	ds_read_b128 v[48:51], v136 offset:32768
	ds_read_b128 v[52:55], v137 offset:32768
	ds_read_b128 v[198:201], v138 offset:32768
	ds_read_b128 v[222:225], v139 offset:32768
	s_waitcnt vmcnt(2)
	s_barrier
; #define LDA(dst, b, h) for (int m = 0; m < 4; ++m) for (int k = 0; k < 2; ++k) \
;     dst[m][k] = *reinterpret_cast<const bf16x8*>((char*)SA(b, h) + lds_byte(wr * 64 + m * 16 + fr, k * 32 + fq * 8))
; #define LDB(dst, b, h) for (int n = 0; n < 2; ++n) for (int k = 0; k < 2; ++k) \
;     dst[n][k] = *reinterpret_cast<const bf16x8*>((char*)SB(b, h) + lds_byte(wc * 32 + n * 16 + fr, k * 32 + fq * 8))
; #define MMA(ai, bj, At_, Bt_) do { __builtin_amdgcn_s_setprio(1); \
;     for (int m = 0; m < 4; ++m) for (int n = 0; n < 2; ++n) for (int k = 0; k < 2; ++k) \
;       acc[ai][bj][m][n] = MFMA16(Bt_[n][k], At_[m][k], acc[ai][bj][m][n]); \
;     __builtin_amdgcn_s_setprio(0); } while (0)
; #define WAIT_V(n) asm volatile("s_waitcnt vmcnt(" #n ")" ::: "memory")
; #define WAIT_L(n) asm volatile("s_waitcnt lgkmcnt(" #n ")" ::: "memory")
; #define BAR __builtin_amdgcn_s_barrier()
; template <int PART  , bool SYNC_FIRST = true>
; __device__ __forceinline__ void kloop_t(const u16* __restrict__ A, int lda, const u16* __restrict__ Bt, int ldb, int K, Acc& acc, const int wv) {
;     ...
;   { LDB(B0, 1, 0); LDA(At, 1, 0); WAIT_V(2); BAR; WAIT_L(0); MMA(0, 0, At, B0); BAR;
;     LDB(B1, 1, 1); WAIT_V(0); BAR; WAIT_L(0); MMA(0, 1, At, B1); BAR;
;     LDA(At, 1, 1); BAR; WAIT_L(0); MMA(1, 0, At, B0); MMA(1, 1, At, B1); BAR; }
;   if (wr == 0) BAR;
	s_waitcnt lgkmcnt(0)
	s_waitcnt lgkmcnt(0)
	v_mfma_f32_16x16x32_bf16 v[64:67], v[0:3], v[16:19], v[124:127]
	v_mfma_f32_16x16x32_bf16 v[112:115], v[4:7], v[20:23], v[64:67]
	v_mfma_f32_16x16x32_bf16 v[64:67], v[194:197], v[16:19], v[120:123]
	v_mfma_f32_16x16x32_bf16 v[116:119], v[174:177], v[20:23], v[64:67]
	v_mfma_f32_16x16x32_bf16 v[64:67], v[0:3], v[32:35], v[166:169]
	v_mfma_f32_16x16x32_bf16 v[96:99], v[4:7], v[36:39], v[64:67]
	v_mfma_f32_16x16x32_bf16 v[64:67], v[194:197], v[32:35], v[206:209]
	v_mfma_f32_16x16x32_bf16 v[100:103], v[174:177], v[36:39], v[64:67]
	v_mfma_f32_16x16x32_bf16 v[64:67], v[0:3], v[48:51], v[108:111]
	v_mfma_f32_16x16x32_bf16 v[80:83], v[4:7], v[52:55], v[64:67]
	v_mfma_f32_16x16x32_bf16 v[64:67], v[194:197], v[48:51], v[104:107]
	v_mfma_f32_16x16x32_bf16 v[84:87], v[174:177], v[52:55], v[64:67]
	v_mfma_f32_16x16x32_bf16 v[64:67], v[0:3], v[198:201], v[210:213]
	v_mfma_f32_16x16x32_bf16 v[68:71], v[194:197], v[198:201], v[214:217]
	v_mfma_f32_16x16x32_bf16 v[64:67], v[4:7], v[222:225], v[64:67]
	v_mfma_f32_16x16x32_bf16 v[68:71], v[174:177], v[222:225], v[68:71]
	s_barrier
	ds_read_b128 v[166:169], v178
	ds_read_b128 v[206:209], v179
	ds_read_b128 v[210:213], v180
	ds_read_b128 v[178:181], v181
	s_waitcnt vmcnt(0)
	s_barrier
	s_waitcnt lgkmcnt(0)
	s_waitcnt lgkmcnt(0)
	v_mfma_f32_16x16x32_bf16 v[92:95], v[166:169], v[16:19], v[92:95]
	v_mfma_f32_16x16x32_bf16 v[16:19], v[210:213], v[16:19], v[88:91]
	v_mfma_f32_16x16x32_bf16 v[124:127], v[178:181], v[20:23], v[16:19]
	v_mfma_f32_16x16x32_bf16 v[16:19], v[166:169], v[32:35], v[158:161]
	v_mfma_f32_16x16x32_bf16 v[104:107], v[206:209], v[36:39], v[16:19]
	v_mfma_f32_16x16x32_bf16 v[16:19], v[210:213], v[32:35], v[162:165]
	v_mfma_f32_16x16x32_bf16 v[108:111], v[178:181], v[36:39], v[16:19]
	v_mfma_f32_16x16x32_bf16 v[16:19], v[166:169], v[48:51], v[76:79]
	v_mfma_f32_16x16x32_bf16 v[88:91], v[206:209], v[52:55], v[16:19]
	v_mfma_f32_16x16x32_bf16 v[16:19], v[210:213], v[48:51], v[72:75]
	v_mfma_f32_16x16x32_bf16 v[120:123], v[206:209], v[20:23], v[92:95]
	v_mfma_f32_16x16x32_bf16 v[92:95], v[178:181], v[52:55], v[16:19]
	v_mfma_f32_16x16x32_bf16 v[16:19], v[166:169], v[198:201], v[170:173]
	v_mfma_f32_16x16x32_bf16 v[72:75], v[206:209], v[222:225], v[16:19]
	v_mfma_f32_16x16x32_bf16 v[16:19], v[210:213], v[198:201], v[182:185]
	v_mfma_f32_16x16x32_bf16 v[76:79], v[178:181], v[222:225], v[16:19]
	s_barrier
	ds_read_b128 v[158:161], v132 offset:49152
	ds_read_b128 v[130:133], v133 offset:49152
	ds_read_b128 v[162:165], v134 offset:49152
	ds_read_b128 v[170:173], v135 offset:49152
	ds_read_b128 v[182:185], v136 offset:49152
	ds_read_b128 v[134:137], v137 offset:49152
	ds_read_b128 v[198:201], v138 offset:49152
	ds_read_b128 v[214:217], v139 offset:49152
	s_barrier
	s_waitcnt lgkmcnt(0)
	s_waitcnt lgkmcnt(0)
	v_mfma_f32_16x16x32_bf16 v[16:19], v[0:3], v[158:161], v[60:63]
	v_mfma_f32_16x16x32_bf16 v[48:51], v[4:7], v[130:133], v[16:19]
	v_mfma_f32_16x16x32_bf16 v[16:19], v[194:197], v[158:161], v[56:59]
	v_mfma_f32_16x16x32_bf16 v[52:55], v[174:177], v[130:133], v[16:19]
	v_mfma_f32_16x16x32_bf16 v[16:19], v[0:3], v[162:165], v[202:205]
	v_mfma_f32_16x16x32_bf16 v[32:35], v[4:7], v[170:173], v[16:19]
	v_mfma_f32_16x16x32_bf16 v[16:19], v[194:197], v[162:165], v[218:221]
	v_mfma_f32_16x16x32_bf16 v[36:39], v[174:177], v[170:173], v[16:19]
	v_mfma_f32_16x16x32_bf16 v[16:19], v[0:3], v[182:185], v[44:47]
	v_mfma_f32_16x16x32_bf16 v[0:3], v[0:3], v[198:201], v[142:145]
	v_mfma_f32_16x16x32_bf16 v[16:19], v[4:7], v[134:137], v[16:19]
	v_mfma_f32_16x16x32_bf16 v[20:23], v[194:197], v[182:185], v[40:43]
	v_mfma_f32_16x16x32_bf16 v[0:3], v[4:7], v[214:217], v[0:3]
	v_mfma_f32_16x16x32_bf16 v[4:7], v[194:197], v[198:201], v[146:149]
	v_mfma_f32_16x16x32_bf16 v[20:23], v[174:177], v[134:137], v[20:23]
	v_mfma_f32_16x16x32_bf16 v[4:7], v[174:177], v[214:217], v[4:7]
	v_mfma_f32_16x16x32_bf16 v[24:27], v[210:213], v[158:161], v[24:27]
	v_mfma_f32_16x16x32_bf16 v[60:63], v[178:181], v[130:133], v[24:27]
	v_mfma_f32_16x16x32_bf16 v[24:27], v[166:169], v[162:165], v[150:153]
	v_mfma_f32_16x16x32_bf16 v[28:31], v[166:169], v[158:161], v[28:31]
	v_mfma_f32_16x16x32_bf16 v[40:43], v[206:209], v[170:173], v[24:27]
	v_mfma_f32_16x16x32_bf16 v[24:27], v[210:213], v[162:165], v[154:157]
	v_mfma_f32_16x16x32_bf16 v[12:15], v[166:169], v[182:185], v[12:15]
	v_mfma_f32_16x16x32_bf16 v[8:11], v[210:213], v[182:185], v[8:11]
	v_mfma_f32_16x16x32_bf16 v[56:59], v[206:209], v[130:133], v[28:31]
	v_mfma_f32_16x16x32_bf16 v[44:47], v[178:181], v[170:173], v[24:27]
	v_mfma_f32_16x16x32_bf16 v[24:27], v[206:209], v[134:137], v[12:15]
	v_mfma_f32_16x16x32_bf16 v[28:31], v[178:181], v[134:137], v[8:11]
	v_mfma_f32_16x16x32_bf16 v[8:11], v[166:169], v[198:201], v[186:189]
	v_mfma_f32_16x16x32_bf16 v[12:15], v[210:213], v[198:201], v[190:193]
	v_mfma_f32_16x16x32_bf16 v[8:11], v[206:209], v[214:217], v[8:11]
	v_mfma_f32_16x16x32_bf16 v[12:15], v[178:181], v[214:217], v[12:15]
	s_andn2_b64 vcc, exec, s[16:17]
	s_barrier
	s_cbranch_vccnz .LBB0_1142
	s_barrier
